# the 128 longest FoX attention items per XCD queue run at s_setprio 2 (they are the mixer phase critical path and were slowed by co-resident waves)
# baseline (speedup 1.0000x reference)
; __global__ void __launch_bounds__(512, 2) mega_fwd(Args a) {
;     ...
;                     const bool issb = (it >= 266 && it < 522), isc = (it >= 522 && it < 618), isfox = !isc && !issb;
;                     if (isfox && !((okmask >> xcd) & 1u)) { unsigned sp = 0u;
;                         while (__hip_atomic_load(done, __ATOMIC_RELAXED, __HIP_MEMORY_SCOPE_AGENT) < 48u) { __builtin_amdgcn_s_sleep(120); if (++sp > (1u << 17)) break; }
;                         __builtin_amdgcn_fence(__ATOMIC_ACQUIRE, "agent"); okmask |= 1u << xcd; }
;                     if (isc && !((okmask >> (8 + xcd)) & 1u)) { unsigned sp = 0u;
;                         while (__hip_atomic_load(done + 8, __ATOMIC_RELAXED, __HIP_MEMORY_SCOPE_AGENT) < 90u) { __builtin_amdgcn_s_sleep(120); if (++sp > (1u << 17)) break; }
;                         __builtin_amdgcn_fence(__ATOMIC_ACQUIRE, "agent"); okmask |= 1u << (8 + xcd); }
;                     if (isc) { const int ci = it - 522; __builtin_amdgcn_s_setprio(2); mlstm_item<true>(ub, yb, mscr, prm + 512, prm + 8, prm + 16, prm + 64, L + wave * ML_WSTRIDE, xcd + 8 * (ci >> 4), 15 - (ci & 15), lane); __builtin_amdgcn_s_setprio(0); }
;                     else { int aitem; if (issb) { const int ai = it - 266; aitem = (ai >> 2) * 80 + 48 + xcd + 8 * (ai & 3); } else { const int ai = (it < 266) ? it - 138 : it - 490; aitem = (ai / 6) * 80 + xcd + 8 * (ai % 6); }
;                         attn_mfma_item(ub, yb, fcl, ftot, L + wave * ML_WSTRIDE, aitem, lane); }
.LBB0_733:
	v_writelane_b32 v255, s48, 17
	s_andn2_b64 vcc, exec, s[0:1]
	s_cbranch_vccnz .LBB0_735
	s_cmpk_lt_i32 s98, 0x10a
	s_movk_i32 s0, 0xff76
	s_cselect_b32 s0, s0, 0xfffffe16
	s_cbranch_scc0 .Lfox_noprio
	s_setprio 2
.Lfox_noprio:
	s_add_i32 s0, s0, s98
	s_mul_hi_i32 s1, s0, 0x2aaaaaab
	s_lshr_b32 s33, s1, 31
	s_add_i32 s1, s1, s33
	s_mul_i32 s33, s1, 0x50
	s_mul_i32 s1, s1, 6
	s_sub_i32 s0, s0, s1
	s_or_b32 s33, s33, s69
	s_lshl_b32 s0, s0, 3
	s_add_i32 s33, s33, s0

; __device__ __forceinline__ unsigned cvtpk(float lo, float hi) { return pg8::cvt_pk_bf16(lo, hi); }
; __device__ __forceinline__ float xh_sum(float x) { auto rr = __builtin_amdgcn_permlane32_swap(__float_as_uint(x), __float_as_uint(x), false, false); return __uint_as_float(rr[0]) + __uint_as_float(rr[1]); }
; __device__ __forceinline__ void attn_mfma_item(const bf16* u, bf16* y, const float* cl, const float* tot, LAS unsigned char* wl, int item, int lane) {
;     ...
;     float inv = 1.0f;
;     if (fox) { lsum = xh_sum(lsum); inv = __builtin_amdgcn_rcpf(lsum); }
;     char* yb0 = (char*)(y + (size_t)b * S * D); const unsigned yo = (unsigned)(t * D + yoff + 4 * hi) * 2u;
; #pragma unroll
;     for (int g = 0; g < 4; ++g) {
;         unsigned long long w0 = (unsigned long long)cvtpk(O0[4 * g] * inv, O0[4 * g + 1] * inv) | ((unsigned long long)cvtpk(O0[4 * g + 2] * inv, O0[4 * g + 3] * inv) << 32);
;         unsigned long long w1 = (unsigned long long)cvtpk(O1[4 * g] * inv, O1[4 * g + 1] * inv) | ((unsigned long long)cvtpk(O1[4 * g + 2] * inv, O1[4 * g + 3] * inv) << 32);
;         *(unsigned long long*)(yb0 + yo + 16 * g) = w0; *(unsigned long long*)(yb0 + yo + 64 + 16 * g) = w1; }
.LBB0_779:
	s_nop 0
	v_mul_f32_e32 v20, v20, v1
	v_mul_f32_e32 v21, v21, v1
	s_lshl_b64 s[0:1], s[0:1], 22
	v_readlane_b32 s50, v253, 47
	v_cvt_pk_bf16_f32 v20, v20, v21
	v_mul_f32_e32 v21, v22, v1
	v_mul_f32_e32 v4, v4, v1
	v_mul_f32_e32 v5, v5, v1
	v_readlane_b32 s51, v253, 48
	s_add_u32 s0, s50, s0
	v_lshl_or_b32 v2, v120, 10, v144
	v_mul_f32_e32 v22, v23, v1
	v_cvt_pk_bf16_f32 v21, v21, v22
	v_cvt_pk_bf16_f32 v4, v4, v5
	v_mul_f32_e32 v5, v6, v1
	s_addc_u32 s1, s51, s1
	v_add_lshl_u32 v2, v2, s2, 1
	v_mul_f32_e32 v6, v7, v1
	v_cvt_pk_bf16_f32 v5, v5, v6
	global_store_dwordx2 v2, v[20:21], s[0:1]
	global_store_dwordx2 v2, v[4:5], s[0:1] offset:64
	v_mul_f32_e32 v4, v24, v1
	v_mul_f32_e32 v5, v25, v1
	v_cvt_pk_bf16_f32 v4, v4, v5
	v_mul_f32_e32 v5, v26, v1
	v_mul_f32_e32 v6, v27, v1
	v_cvt_pk_bf16_f32 v5, v5, v6
	v_mul_f32_e32 v6, v8, v1
	v_mul_f32_e32 v7, v9, v1
	v_cvt_pk_bf16_f32 v6, v6, v7
	v_mul_f32_e32 v7, v10, v1
	v_mul_f32_e32 v8, v11, v1
	v_cvt_pk_bf16_f32 v7, v7, v8
	global_store_dwordx2 v2, v[4:5], s[0:1] offset:16
	global_store_dwordx2 v2, v[6:7], s[0:1] offset:80
	v_mul_f32_e32 v4, v28, v1
	v_mul_f32_e32 v5, v29, v1
	v_cvt_pk_bf16_f32 v4, v4, v5
	v_mul_f32_e32 v5, v30, v1
	v_mul_f32_e32 v6, v31, v1
	v_cvt_pk_bf16_f32 v5, v5, v6
	v_mul_f32_e32 v6, v12, v1
	v_mul_f32_e32 v7, v13, v1
	v_cvt_pk_bf16_f32 v6, v6, v7
	v_mul_f32_e32 v7, v14, v1
	v_mul_f32_e32 v8, v15, v1
	v_cvt_pk_bf16_f32 v7, v7, v8
	global_store_dwordx2 v2, v[4:5], s[0:1] offset:32
	global_store_dwordx2 v2, v[6:7], s[0:1] offset:96
	v_mul_f32_e32 v4, v32, v1
	v_mul_f32_e32 v5, v33, v1
	v_cvt_pk_bf16_f32 v4, v4, v5
	v_mul_f32_e32 v5, v34, v1
	v_mul_f32_e32 v6, v35, v1
	v_cvt_pk_bf16_f32 v5, v5, v6
	v_mul_f32_e32 v6, v16, v1
	v_mul_f32_e32 v7, v17, v1
	s_mov_b64 s[22:23], s[24:25]
	s_mov_b64 s[24:25], s[26:27]
	v_readlane_b32 s26, v254, 59
	v_readlane_b32 s28, v254, 57
	v_readlane_b32 s30, v254, 55
	v_readlane_b32 s34, v254, 53
	v_readlane_b32 s36, v254, 51
	v_readlane_b32 s38, v254, 49
	v_readlane_b32 s40, v254, 47
	v_readlane_b32 s42, v254, 45
	v_cvt_pk_bf16_f32 v6, v6, v7
	v_mul_f32_e32 v7, v18, v1
	s_movk_i32 s88, 0x4000
	s_mov_b64 s[92:93], 0x80
	v_readlane_b32 s27, v254, 60
	v_readlane_b32 s29, v254, 58
	v_readlane_b32 s31, v254, 56
	v_readlane_b32 s35, v254, 54
	v_readlane_b32 s37, v254, 52
	v_readlane_b32 s39, v254, 50
	v_readlane_b32 s41, v254, 48
	v_readlane_b32 s43, v254, 46
	v_mul_f32_e32 v1, v19, v1
	v_cvt_pk_bf16_f32 v7, v7, v1
	global_store_dwordx2 v2, v[4:5], s[0:1] offset:48
	global_store_dwordx2 v2, v[6:7], s[0:1] offset:112
	s_setprio 0
	s_branch .LBB0_795
